# gnorm loop and prologue x->bf16 loop both software-pipelined two rows ahead
# speedup vs baseline: 1.0015x; 1.0013x over previous
.LBB0_73:
	s_waitcnt lgkmcnt(0)
	s_mov_b32 s98, 0
	global_load_dwordx4 v[104:107], v[6:7], off offset:-3072
	global_load_dwordx4 v[108:111], v[6:7], off offset:-2048
	global_load_dwordx4 v[112:115], v[6:7], off offset:-1024
	global_load_dwordx4 v[116:119], v[6:7], off
	v_lshl_add_u64 v[6:7], v[6:7], 0, s[14:15]
	s_add_i32 s99, s8, s26
	s_cmp_gt_i32 s99, 0xffff
	s_cbranch_scc1 .Lxn_loop
	global_load_dwordx4 v[120:123], v[6:7], off offset:-3072
	global_load_dwordx4 v[124:127], v[6:7], off offset:-2048
	global_load_dwordx4 v[128:131], v[6:7], off offset:-1024
	global_load_dwordx4 v[132:135], v[6:7], off
	v_lshl_add_u64 v[6:7], v[6:7], 0, s[14:15]
.Lxn_loop:
	s_waitcnt lgkmcnt(0)
	s_add_i32 s99, s8, s26
	s_cmp_gt_i32 s99, 0xffff
	s_cselect_b32 s100, 0, 4
	s_min_u32 s101, s98, 2
	s_mul_i32 s101, s101, 5
	s_add_i32 s100, s100, s101
	s_cmp_eq_u32 s100, 14
	s_cbranch_scc1 .Lxn_w14
	s_cmp_eq_u32 s100, 10
	s_cbranch_scc1 .Lxn_w10
	s_cmp_eq_u32 s100, 9
	s_cbranch_scc1 .Lxn_w9
	s_cmp_eq_u32 s100, 5
	s_cbranch_scc1 .Lxn_w5
	s_cmp_eq_u32 s100, 4
	s_cbranch_scc1 .Lxn_w4
	s_waitcnt vmcnt(0)
	s_branch .Lxn_wd
.Lxn_w14:
	s_waitcnt vmcnt(14)
	s_branch .Lxn_wd
.Lxn_w10:
	s_waitcnt vmcnt(10)
	s_branch .Lxn_wd
.Lxn_w9:
	s_waitcnt vmcnt(9)
	s_branch .Lxn_wd
.Lxn_w5:
	s_waitcnt vmcnt(5)
	s_branch .Lxn_wd

.Lxn_wd:
	s_add_i32 s99, s99, s26
	s_cmp_gt_i32 s99, 0xffff
	s_cselect_b32 s101, 0, 1
	s_bitcmp1_b32 s98, 0
	s_cbranch_scc1 .Lxn_odd
	v_mov_b64_e32 v[16:17], v[104:105]
	v_mov_b64_e32 v[18:19], v[106:107]
	v_mov_b64_e32 v[20:21], v[108:109]
	v_mov_b64_e32 v[22:23], v[110:111]
	v_mov_b64_e32 v[24:25], v[112:113]
	v_mov_b64_e32 v[26:27], v[114:115]
	v_mov_b64_e32 v[28:29], v[116:117]
	v_mov_b64_e32 v[30:31], v[118:119]
	s_cmp_eq_u32 s101, 0
	s_cbranch_scc1 .Lxn_body
	global_load_dwordx4 v[104:107], v[6:7], off offset:-3072
	global_load_dwordx4 v[108:111], v[6:7], off offset:-2048
	global_load_dwordx4 v[112:115], v[6:7], off offset:-1024
	global_load_dwordx4 v[116:119], v[6:7], off
	v_lshl_add_u64 v[6:7], v[6:7], 0, s[14:15]
	s_branch .Lxn_body
.Lxn_odd:
	v_mov_b64_e32 v[16:17], v[120:121]
	v_mov_b64_e32 v[18:19], v[122:123]
	v_mov_b64_e32 v[20:21], v[124:125]
	v_mov_b64_e32 v[22:23], v[126:127]
	v_mov_b64_e32 v[24:25], v[128:129]
	v_mov_b64_e32 v[26:27], v[130:131]
	v_mov_b64_e32 v[28:29], v[132:133]
	v_mov_b64_e32 v[30:31], v[134:135]
	s_cmp_eq_u32 s101, 0
	s_cbranch_scc1 .Lxn_body
	global_load_dwordx4 v[120:123], v[6:7], off offset:-3072
	global_load_dwordx4 v[124:127], v[6:7], off offset:-2048
	global_load_dwordx4 v[128:131], v[6:7], off offset:-1024
	global_load_dwordx4 v[132:135], v[6:7], off
	v_lshl_add_u64 v[6:7], v[6:7], 0, s[14:15]
.Lxn_body:
	v_mul_f32_e32 v15, v17, v17
	v_mul_f32_e32 v32, v19, v19
	v_mul_f32_e32 v33, v21, v21
	v_mul_f32_e32 v34, v23, v23
	v_mul_f32_e32 v35, v25, v25
	v_mul_f32_e32 v36, v27, v27
	v_fmac_f32_e32 v15, v16, v16
	v_fmac_f32_e32 v32, v18, v18
	v_fmac_f32_e32 v33, v20, v20
	v_fmac_f32_e32 v34, v22, v22
	v_mul_f32_e32 v37, v29, v29
	v_mul_f32_e32 v38, v31, v31
	v_fmac_f32_e32 v35, v24, v24
	v_fmac_f32_e32 v36, v26, v26
	v_add_f32_e32 v15, v15, v32
	v_add_f32_e32 v32, v33, v34
	v_fmac_f32_e32 v37, v28, v28
	v_fmac_f32_e32 v38, v30, v30
	v_add_f32_e32 v33, v35, v36
	v_add_f32_e32 v15, v15, v32
	v_add_f32_e32 v34, v37, v38
	v_add_f32_e32 v15, v15, v33
	v_add_f32_e32 v15, v15, v34
	ds_bpermute_b32 v32, v8, v15
	v_cvt_pk_bf16_f32 v16, v16, v17
	v_cvt_pk_bf16_f32 v17, v18, v19
	v_cvt_pk_bf16_f32 v18, v20, v21
	v_cvt_pk_bf16_f32 v19, v22, v23
	s_waitcnt lgkmcnt(0)
	v_add_f32_e32 v15, v15, v32
	ds_bpermute_b32 v32, v9, v15
	v_cvt_pk_bf16_f32 v20, v24, v25
	s_waitcnt lgkmcnt(0)
	v_add_f32_e32 v15, v15, v32
	ds_bpermute_b32 v34, v11, v15
	v_lshl_add_u64 v[32:33], s[18:19], 0, v[4:5]
	v_add_co_u32_e64 v32, s[0:1], s9, v32
	s_waitcnt lgkmcnt(0)
	v_add_f32_e32 v15, v15, v34
	ds_bpermute_b32 v34, v12, v15
	v_addc_co_u32_e64 v33, s[0:1], 0, v33, s[0:1]
	global_store_dwordx2 v[32:33], v[16:17], off
	global_store_dwordx2 v[32:33], v[18:19], off offset:512
	v_cvt_pk_bf16_f32 v18, v28, v29
	s_waitcnt lgkmcnt(0)
	v_add_f32_e32 v15, v15, v34
	ds_bpermute_b32 v21, v13, v15
	v_cvt_pk_bf16_f32 v19, v30, v31
	global_store_dwordx2 v[32:33], v[18:19], off offset:1536
	s_waitcnt lgkmcnt(0)
	v_add_f32_e32 v15, v15, v21
	ds_bpermute_b32 v16, v14, v15
	v_cvt_pk_bf16_f32 v21, v26, v27
	global_store_dwordx2 v[32:33], v[20:21], off offset:1024
	s_and_saveexec_b64 s[0:1], vcc
	s_cbranch_execz .LBB0_72
	s_waitcnt lgkmcnt(0)
	v_add_f32_e32 v15, v15, v16
	v_cndmask_b32_e64 v15, 0, v15, s[4:5]
	v_lshl_add_u64 v[16:17], s[18:19], 0, v[2:3]
	global_store_dword v[16:17], v15, off
.LBB0_72:
	s_or_b64 exec, exec, s[0:1]
	s_add_i32 s8, s8, s26
	v_lshl_add_u64 v[2:3], v[2:3], 0, s[6:7]
	v_lshl_add_u64 v[4:5], v[4:5], 0, s[12:13]
	s_add_i32 s98, s98, 1
	s_cmp_gt_i32 s8, 0xffff
	s_cbranch_scc0 .Lxn_loop
